# P2: item-top vmcnt(0) relaxed to vmcnt(4) so the last task's output stores are not waited before staging the next item
# baseline (speedup 1.0000x reference)
; #define LAS __attribute__((address_space(3)))
; #define ATT_QPTR(I, i_) (Z + ((size_t)((I).qslot0() + ((I).isA ? ((wave * 4 + (i_)) >> 3) : 0)) * TT + (I).seq0 + (I).res * (I).Lr + (I).j0 + 16 * ATT_QT(I, i_) + qi) * 64)
;     ...
;     const int nloc = nA + nB, r0 = tid >> 3, ch = tid & 7;
;     v4u pk[6], pv[6];
;     ...
;     if (nloc <= 0) return;
;     Item cur = decode(0, na0, nA, nb0), nxt = cur;
;     ...
;     bf16x8 q0, q1;
;     { const bf16* qp = ATT_QPTR(cur, 0); q0 = *(const bf16x8*)(qp + g * 8); q1 = *(const bf16x8*)(qp + 32 + g * 8); }
;     asm volatile("" ::: "memory");
;     ATT_ISSUE(cur);
;     int tkey = -1;
;     for (int k = 0; k < nloc; ++k) {
;         __syncthreads();
; #pragma unroll
;         for (int i = 0; i < 6; ++i) { const int row = r0 + 64 * i; *(LAS v4u*)(ldsK + row * KRS + ch * 16) = pk[i]; *(LAS v4u*)(ldsV + row * VRS + ch * 16) = pv[i];
;             if (ch == 0) { const unsigned kp = (unsigned)(cur.j0 - cur.n() + row); const float ninf = -__builtin_inff();
;                 pmt[row] = (kp < (unsigned)(cur.pair ? cur.Lr : cur.Lre)) ? 0.f : ninf;
;                 pmt[NKS_MAX + row] = (cur.pair ? (kp - (unsigned)cur.Lr < (unsigned)cur.Lr) : (kp < (unsigned)cur.Lre)) ? 0.f : ninf; } }
.LBB0_178:
	s_or_b64 exec, exec, s[8:9]
	v_lshlrev_b32_e32 v0, 3, v144
	v_and_b32_e32 v0, 24, v0
	v_mov_b32_e32 v63, v21
	s_movk_i32 s78, 0x90
	s_movk_i32 s79, 0xa0
	v_lshl_add_u32 v175, v117, 4, 0
	v_lshlrev_b32_e32 v148, 2, v116
	v_add_u32_e32 v150, 0, v0
	v_lshl_add_u64 v[152:153], s[20:21], 0, v[62:63]
	v_mul_lo_u32 v0, v151, s78
	v_mul_lo_u32 v63, v151, s79
	s_add_i32 s0, 0, 0x1f000
	v_add_u32_e32 v180, 64, v151
	v_add_u32_e32 v1, 0x2800, v63
	v_add_u32_e32 v182, 0x80, v151
	v_add_u32_e32 v2, 0x5000, v63
	v_add_u32_e32 v184, 0xc0, v151
	v_add_u32_e32 v3, 0x7800, v63
	v_add_u32_e32 v186, 0x100, v151
	v_add_u32_e32 v4, 0xa000, v63
	v_add_u32_e32 v188, 0x140, v151
	v_add_u32_e32 v5, 0xc800, v63
	v_sub_u32_e32 v6, v148, v144
	v_add_u32_e32 v242, 4, v151
	v_bfe_u32 v242, v242, 3, 1
	v_xor_b32_e32 v242, v242, v117
	v_lshl_add_u32 v193, v242, 4, v0
	v_mbcnt_lo_u32_b32 v0, -1, 0
	v_mov_b32_e32 v145, v16
	v_cmp_ne_u32_e64 s[8:9], 0, v117
	s_lshl_b32 s77, s49, 2
	v_add_u32_e32 v243, 4, v144
	v_bfe_u32 v243, v243, 3, 1
	v_xor_b32_e32 v243, v243, v116
	v_lshlrev_b32_e32 v146, 4, v243
	v_and_b32_e32 v253, 1, v144
	v_mul_u32_u24_e32 v253, 0x3884, v253
	v_lshrrev_b32_e32 v178, 2, v144
	v_mov_b32_e32 v149, v21
	v_cmp_eq_u32_e64 s[4:5], 0, v116
	v_lshl_add_u32 v179, v151, 2, s0
	v_lshl_add_u32 v181, v180, 2, s0
	v_lshl_add_u32 v183, v182, 2, s0
	v_lshl_add_u32 v185, v184, 2, s0
	v_lshl_add_u32 v187, v186, 2, s0
	v_lshl_add_u32 v189, v188, 2, s0
	s_lshl_b32 s80, s49, 1
	v_subrev_u32_e32 v190, s73, v6
	s_mov_b32 s66, -1
	s_mov_b32 s81, 0xff800000
	v_add_u32_e32 v191, v175, v2
	v_add_u32_e32 v192, v175, v4
	s_movk_i32 s82, 0x280
	s_add_i32 s83, 0, 0x1c800
	v_add_u32_e32 v194, v175, v1
	v_mov_b32_e32 v195, 0xff800000
	v_add_u32_e32 v197, v175, v3
	v_add_u32_e32 v198, v175, v5
	v_mov_b32_e32 v56, 0
	v_mbcnt_hi_u32_b32 v199, -1, v0
	v_mov_b32_e32 v200, 0x42000000
	s_mov_b32 s84, 0
	s_waitcnt vmcnt(0)
	s_branch .LBB0_180

; #define LAS __attribute__((address_space(3)))
;     ...
;     for (int k = 0; k < nloc; ++k) {
;         __syncthreads();
; #pragma unroll
;         for (int i = 0; i < 6; ++i) { const int row = r0 + 64 * i; *(LAS v4u*)(ldsK + row * KRS + ch * 16) = pk[i]; *(LAS v4u*)(ldsV + row * VRS + ch * 16) = pv[i];
;             if (ch == 0) { const unsigned kp = (unsigned)(cur.j0 - cur.n() + row); const float ninf = -__builtin_inff();
;                 pmt[row] = (kp < (unsigned)(cur.pair ? cur.Lr : cur.Lre)) ? 0.f : ninf;
;                 pmt[NKS_MAX + row] = (cur.pair ? (kp - (unsigned)cur.Lr < (unsigned)cur.Lr) : (kp < (unsigned)cur.Lre)) ? 0.f : ninf; } }
.LBB0_180:
	s_cmp_lg_u32 s70, 0
	s_cselect_b64 s[48:49], -1, 0
	s_cmp_eq_u32 s70, 0
	s_cselect_b64 s[50:51], -1, 0
	s_and_b64 s[0:1], s[50:51], exec
	s_movk_i32 s0, 0xffc0
	s_cselect_b32 s0, s0, 0xffffff80
	s_cmp_lg_u32 s75, 0
	s_cselect_b64 s[54:55], -1, 0
	s_cmp_eq_u32 s75, 0
	s_cselect_b64 s[6:7], -1, 0
	s_and_b64 s[56:57], s[6:7], exec
	s_cselect_b32 s58, s74, s98
	v_add_u32_e32 v0, v175, v63
	s_barrier
	ds_write_b128 v193, v[24:27]
	s_waitcnt vmcnt(4)
	ds_write_b128 v0, v[92:95] offset:55296
	s_and_saveexec_b64 s[56:57], s[8:9]
	s_xor_b64 s[56:57], exec, s[56:57]
	s_cbranch_execz .LBB0_182
	ds_write_b128 v193, v[28:31] offset:9216
	ds_write_b128 v194, v[96:99] offset:55296
